# v47 + G3/G4 mid-K rescale: 16 scale-vector loads of the first two quarters issued as one batch with counted waits (E1 only)
# baseline (speedup 1.0000x reference)
; __device__ __forceinline__ float bf_lo(unsigned u) { return __uint_as_float(u << 16); }
; __device__ __forceinline__ float bf_hi(unsigned u) { return __uint_as_float(u & 0xffff0000u); }
;     __device__ __forceinline__ void mid(f32x4 (&acc)[2][2][4][2], const Unit& u, int wr, int wc, int fr, int fq) const {
;         unsigned off = (unsigned)(u.pm * BM + wr * 64 + fr) * 2048u + (unsigned)(u.pn * BM + wc * 32 + 8 * fq);
; #pragma unroll
;         for (int ai = 0; ai < 2; ++ai) {
;             asm volatile("" : "+v"(off) :: "memory");
;             u32x4 sa[4][2], sb[4][2];
; #pragma unroll
;             for (int m = 0; m < 4; ++m)
; #pragma unroll
;                 for (int bj = 0; bj < 2; ++bj) { sa[m][bj] = *(const u32x4*)(sg + off + m * 16 * 2048 + bj * HALF); sb[m][bj] = *(const u32x4*)(sg + off + m * 16 * 2048 + 1024 + bj * HALF); }
; #pragma unroll
;             for (int m = 0; m < 4; ++m)
; #pragma unroll
;                 for (int bj = 0; bj < 2; ++bj) {
;                     const unsigned av[4] = {sa[m][bj].x, sa[m][bj].y, sa[m][bj].z, sa[m][bj].w}, bv[4] = {sb[m][bj].x, sb[m][bj].y, sb[m][bj].z, sb[m][bj].w};
; #pragma unroll
;                     for (int q = 0; q < 4; ++q) { const float r0 = bf_lo(av[q]) * __builtin_amdgcn_rcpf(fmaxf(bf_lo(bv[q]), 1e-30f)), r1 = bf_hi(av[q]) * __builtin_amdgcn_rcpf(fmaxf(bf_hi(bv[q]), 1e-30f));
;                         acc[ai][bj][m][q >> 1][(q & 1) * 2] *= r0; acc[ai][bj][m][q >> 1][(q & 1) * 2 + 1] *= r1; } }
;             off += 128u * 2048u; }
.LBB0_423:
	s_cmpk_lg_i32 s26, 0x400
	s_cbranch_scc1 .LBB0_422
	v_mov_b32_e32 v194, v218
	s_nop 0
	v_lshl_add_u64 v[128:129], v[194:195], 1, s[10:11]
	global_load_dwordx4 v[184:187], v[128:129], off
	global_load_dwordx4 v[188:191], v[128:129], off offset:2048
	global_load_dwordx4 v[176:179], v[128:129], off offset:256
	global_load_dwordx4 v[180:183], v[128:129], off offset:2304
	v_add_co_u32_e32 v130, vcc, s72, v128
	v_add_u32_e32 v194, 0x40000, v194
	s_nop 0
	v_addc_co_u32_e32 v131, vcc, 0, v129, vcc
	global_load_dwordx4 v[168:171], v[130:131], off
	global_load_dwordx4 v[172:175], v[130:131], off offset:2048
	global_load_dwordx4 v[160:163], v[130:131], off offset:256
	global_load_dwordx4 v[164:167], v[130:131], off offset:2304
	v_add_co_u32_e32 v134, vcc, s43, v128
	s_nop 1
	v_addc_co_u32_e32 v135, vcc, 0, v129, vcc
	global_load_dwordx4 v[152:155], v[134:135], off
	global_load_dwordx4 v[156:159], v[134:135], off offset:2048
	global_load_dwordx4 v[144:147], v[134:135], off offset:256
	global_load_dwordx4 v[148:151], v[134:135], off offset:2304
	v_add_co_u32_e32 v132, vcc, s60, v128
	s_nop 1
	v_addc_co_u32_e32 v133, vcc, 0, v129, vcc
	global_load_dwordx4 v[136:139], v[132:133], off
	global_load_dwordx4 v[140:143], v[132:133], off offset:2048
	global_load_dwordx4 v[128:131], v[132:133], off offset:256
	s_nop 0
	global_load_dwordx4 v[132:135], v[132:133], off offset:2304
	s_waitcnt vmcnt(15)
	v_lshlrev_b32_e32 v240, 16, v184
	s_waitcnt vmcnt(14)
	v_lshlrev_b32_e32 v219, 16, v188
	v_and_b32_e32 v188, 0xffff0000, v188
	v_and_b32_e32 v241, 0xffff0000, v184
	v_lshlrev_b32_e32 v184, 16, v189
	v_max_f32_e32 v188, v188, v188
	v_max_f32_e32 v184, v184, v184
	v_max_f32_e32 v188, 0xda24260, v188
	v_max_f32_e32 v184, 0xda24260, v184
	v_rcp_f32_e32 v239, v188
	v_rcp_f32_e32 v188, v184
	v_and_b32_e32 v184, 0xffff0000, v189
	v_max_f32_e32 v184, v184, v184
	v_max_f32_e32 v184, 0xda24260, v184
	v_rcp_f32_e32 v189, v184
	v_lshlrev_b32_e32 v184, 16, v185
	v_and_b32_e32 v185, 0xffff0000, v185
	v_pk_mul_f32 v[184:185], v[188:189], v[184:185]
	v_lshlrev_b32_e32 v188, 16, v186
	v_pk_mul_f32 v[126:127], v[126:127], v[184:185]
	v_lshlrev_b32_e32 v184, 16, v190
	v_and_b32_e32 v185, 0xffff0000, v190
	v_max_f32_e32 v184, v184, v184
	v_max_f32_e32 v185, v185, v185
	v_max_f32_e32 v184, 0xda24260, v184
	v_max_f32_e32 v185, 0xda24260, v185
	v_rcp_f32_e32 v184, v184
	v_rcp_f32_e32 v185, v185
	v_and_b32_e32 v189, 0xffff0000, v186
	v_lshlrev_b32_e32 v186, 16, v187
	v_and_b32_e32 v187, 0xffff0000, v187
	v_pk_mul_f32 v[184:185], v[184:185], v[188:189]
	v_pk_mul_f32 v[120:121], v[120:121], v[184:185]
	v_lshlrev_b32_e32 v184, 16, v191
	v_and_b32_e32 v185, 0xffff0000, v191
	v_max_f32_e32 v184, v184, v184
	v_max_f32_e32 v185, v185, v185
	v_max_f32_e32 v184, 0xda24260, v184
	v_max_f32_e32 v185, 0xda24260, v185
	v_rcp_f32_e32 v184, v184
	v_rcp_f32_e32 v185, v185
	v_max_f32_e32 v219, v219, v219
	v_pk_mul_f32 v[184:185], v[184:185], v[186:187]
	s_waitcnt vmcnt(13)
	v_lshlrev_b32_e32 v186, 16, v176
	v_pk_mul_f32 v[122:123], v[122:123], v[184:185]
	s_waitcnt vmcnt(12)
	v_lshlrev_b32_e32 v184, 16, v180
	v_and_b32_e32 v180, 0xffff0000, v180
	v_and_b32_e32 v187, 0xffff0000, v176
	v_lshlrev_b32_e32 v176, 16, v181
	v_max_f32_e32 v180, v180, v180
	v_max_f32_e32 v176, v176, v176
	v_max_f32_e32 v180, 0xda24260, v180
	v_max_f32_e32 v176, 0xda24260, v176
	v_rcp_f32_e32 v185, v180
	v_rcp_f32_e32 v180, v176
	v_and_b32_e32 v176, 0xffff0000, v181
	v_max_f32_e32 v176, v176, v176
	v_max_f32_e32 v176, 0xda24260, v176
	v_rcp_f32_e32 v181, v176
	v_lshlrev_b32_e32 v176, 16, v177
	v_and_b32_e32 v177, 0xffff0000, v177
	v_pk_mul_f32 v[176:177], v[180:181], v[176:177]
	v_lshlrev_b32_e32 v180, 16, v178
	v_pk_mul_f32 v[118:119], v[118:119], v[176:177]
	v_lshlrev_b32_e32 v176, 16, v182
	v_and_b32_e32 v177, 0xffff0000, v182
	v_max_f32_e32 v176, v176, v176
	v_max_f32_e32 v177, v177, v177
	v_max_f32_e32 v176, 0xda24260, v176
	v_max_f32_e32 v177, 0xda24260, v177
	v_rcp_f32_e32 v176, v176
	v_rcp_f32_e32 v177, v177
	v_and_b32_e32 v181, 0xffff0000, v178
	v_lshlrev_b32_e32 v178, 16, v179
	v_and_b32_e32 v179, 0xffff0000, v179
	v_pk_mul_f32 v[176:177], v[176:177], v[180:181]
	v_pk_mul_f32 v[112:113], v[112:113], v[176:177]
	v_lshlrev_b32_e32 v176, 16, v183
	v_and_b32_e32 v177, 0xffff0000, v183
	v_max_f32_e32 v176, v176, v176
	v_max_f32_e32 v177, v177, v177
	v_max_f32_e32 v176, 0xda24260, v176
	v_max_f32_e32 v177, 0xda24260, v177
	v_rcp_f32_e32 v176, v176
	v_rcp_f32_e32 v177, v177
	v_max_f32_e32 v184, v184, v184
	v_max_f32_e32 v184, 0xda24260, v184
	v_pk_mul_f32 v[176:177], v[176:177], v[178:179]
	s_waitcnt vmcnt(11)
	v_lshlrev_b32_e32 v178, 16, v168
	v_pk_mul_f32 v[114:115], v[114:115], v[176:177]
	s_waitcnt vmcnt(10)
	v_lshlrev_b32_e32 v176, 16, v172
	v_and_b32_e32 v172, 0xffff0000, v172
	v_and_b32_e32 v179, 0xffff0000, v168
	v_lshlrev_b32_e32 v168, 16, v173
	v_max_f32_e32 v172, v172, v172
	v_max_f32_e32 v168, v168, v168
	v_max_f32_e32 v172, 0xda24260, v172
	v_max_f32_e32 v168, 0xda24260, v168
	v_rcp_f32_e32 v177, v172
	v_rcp_f32_e32 v172, v168
	v_and_b32_e32 v168, 0xffff0000, v173
	v_max_f32_e32 v168, v168, v168
	v_max_f32_e32 v168, 0xda24260, v168
	v_rcp_f32_e32 v173, v168
	v_lshlrev_b32_e32 v168, 16, v169
	v_and_b32_e32 v169, 0xffff0000, v169
	v_max_f32_e32 v176, v176, v176
	v_pk_mul_f32 v[168:169], v[172:173], v[168:169]
	v_lshlrev_b32_e32 v172, 16, v170
	v_pk_mul_f32 v[110:111], v[110:111], v[168:169]
	v_lshlrev_b32_e32 v168, 16, v174
	v_and_b32_e32 v169, 0xffff0000, v174
	v_max_f32_e32 v168, v168, v168
	v_max_f32_e32 v169, v169, v169
	v_max_f32_e32 v168, 0xda24260, v168
	v_max_f32_e32 v169, 0xda24260, v169
	v_rcp_f32_e32 v168, v168
	v_rcp_f32_e32 v169, v169
	v_and_b32_e32 v173, 0xffff0000, v170
	v_lshlrev_b32_e32 v170, 16, v171
	v_and_b32_e32 v171, 0xffff0000, v171
	v_pk_mul_f32 v[168:169], v[168:169], v[172:173]
	v_max_f32_e32 v176, 0xda24260, v176
	v_pk_mul_f32 v[104:105], v[104:105], v[168:169]
	v_lshlrev_b32_e32 v168, 16, v175
	v_and_b32_e32 v169, 0xffff0000, v175
	v_max_f32_e32 v168, v168, v168
	v_max_f32_e32 v169, v169, v169
	v_max_f32_e32 v168, 0xda24260, v168
	v_max_f32_e32 v169, 0xda24260, v169
	v_rcp_f32_e32 v168, v168
	v_rcp_f32_e32 v169, v169
	v_rcp_f32_e32 v176, v176
	v_rcp_f32_e32 v184, v184
	v_max_f32_e32 v219, 0xda24260, v219
	v_pk_mul_f32 v[168:169], v[168:169], v[170:171]
	s_waitcnt vmcnt(9)
; __device__ __forceinline__ float bf_lo(unsigned u) { return __uint_as_float(u << 16); }
; __device__ __forceinline__ float bf_hi(unsigned u) { return __uint_as_float(u & 0xffff0000u); }
;     __device__ __forceinline__ void mid(f32x4 (&acc)[2][2][4][2], const Unit& u, int wr, int wc, int fr, int fq) const {
;     ...
;             for (int m = 0; m < 4; ++m)
; #pragma unroll
;                 for (int bj = 0; bj < 2; ++bj) {
;                     const unsigned av[4] = {sa[m][bj].x, sa[m][bj].y, sa[m][bj].z, sa[m][bj].w}, bv[4] = {sb[m][bj].x, sb[m][bj].y, sb[m][bj].z, sb[m][bj].w};
; #pragma unroll
;                     for (int q = 0; q < 4; ++q) { const float r0 = bf_lo(av[q]) * __builtin_amdgcn_rcpf(fmaxf(bf_lo(bv[q]), 1e-30f)), r1 = bf_hi(av[q]) * __builtin_amdgcn_rcpf(fmaxf(bf_hi(bv[q]), 1e-30f));
;                         acc[ai][bj][m][q >> 1][(q & 1) * 2] *= r0; acc[ai][bj][m][q >> 1][(q & 1) * 2 + 1] *= r1; } }
	v_lshlrev_b32_e32 v170, 16, v160
	v_pk_mul_f32 v[106:107], v[106:107], v[168:169]
	s_waitcnt vmcnt(8)
	v_lshlrev_b32_e32 v168, 16, v164
	v_and_b32_e32 v164, 0xffff0000, v164
	v_and_b32_e32 v171, 0xffff0000, v160
	v_lshlrev_b32_e32 v160, 16, v165
	v_max_f32_e32 v164, v164, v164
	v_max_f32_e32 v160, v160, v160
	v_max_f32_e32 v164, 0xda24260, v164
	v_max_f32_e32 v160, 0xda24260, v160
	v_rcp_f32_e32 v169, v164
	v_rcp_f32_e32 v164, v160
	v_and_b32_e32 v160, 0xffff0000, v165
	v_max_f32_e32 v160, v160, v160
	v_max_f32_e32 v160, 0xda24260, v160
	v_rcp_f32_e32 v165, v160
	v_lshlrev_b32_e32 v160, 16, v161
	v_and_b32_e32 v161, 0xffff0000, v161
	v_pk_mul_f32 v[176:177], v[176:177], v[178:179]
	v_pk_mul_f32 v[160:161], v[164:165], v[160:161]
	v_lshlrev_b32_e32 v164, 16, v162
	v_pk_mul_f32 v[102:103], v[102:103], v[160:161]
	v_lshlrev_b32_e32 v160, 16, v166
	v_and_b32_e32 v161, 0xffff0000, v166
	v_max_f32_e32 v160, v160, v160
	v_max_f32_e32 v161, v161, v161
	v_max_f32_e32 v160, 0xda24260, v160
	v_max_f32_e32 v161, 0xda24260, v161
	v_rcp_f32_e32 v160, v160
	v_rcp_f32_e32 v161, v161
	v_and_b32_e32 v165, 0xffff0000, v162
	v_lshlrev_b32_e32 v162, 16, v163
	v_and_b32_e32 v163, 0xffff0000, v163
	v_pk_mul_f32 v[160:161], v[160:161], v[164:165]
	v_pk_mul_f32 v[108:109], v[108:109], v[176:177]
	v_pk_mul_f32 v[92:93], v[92:93], v[160:161]
	v_lshlrev_b32_e32 v160, 16, v167
	v_and_b32_e32 v161, 0xffff0000, v167
	v_max_f32_e32 v160, v160, v160
	v_max_f32_e32 v161, v161, v161
	v_max_f32_e32 v160, 0xda24260, v160
	v_max_f32_e32 v161, 0xda24260, v161
	v_rcp_f32_e32 v160, v160
	v_rcp_f32_e32 v161, v161
	v_max_f32_e32 v168, v168, v168
	v_max_f32_e32 v168, 0xda24260, v168
	v_rcp_f32_e32 v168, v168
	v_pk_mul_f32 v[160:161], v[160:161], v[162:163]
	s_waitcnt vmcnt(7)
	v_lshlrev_b32_e32 v162, 16, v152
	v_pk_mul_f32 v[94:95], v[94:95], v[160:161]
	s_waitcnt vmcnt(6)
	v_lshlrev_b32_e32 v160, 16, v156
	v_and_b32_e32 v156, 0xffff0000, v156
	v_and_b32_e32 v163, 0xffff0000, v152
	v_lshlrev_b32_e32 v152, 16, v157
	v_max_f32_e32 v156, v156, v156
	v_max_f32_e32 v152, v152, v152
	v_max_f32_e32 v156, 0xda24260, v156
	v_max_f32_e32 v152, 0xda24260, v152
	v_rcp_f32_e32 v161, v156
	v_rcp_f32_e32 v156, v152
	v_and_b32_e32 v152, 0xffff0000, v157
	v_max_f32_e32 v152, v152, v152
	v_max_f32_e32 v152, 0xda24260, v152
	v_rcp_f32_e32 v157, v152
	v_lshlrev_b32_e32 v152, 16, v153
	v_and_b32_e32 v153, 0xffff0000, v153
	v_max_f32_e32 v160, v160, v160
	v_pk_mul_f32 v[152:153], v[156:157], v[152:153]
	v_lshlrev_b32_e32 v156, 16, v154
	v_pk_mul_f32 v[98:99], v[98:99], v[152:153]
	v_lshlrev_b32_e32 v152, 16, v158
	v_and_b32_e32 v153, 0xffff0000, v158
	v_max_f32_e32 v152, v152, v152
	v_max_f32_e32 v153, v153, v153
	v_max_f32_e32 v152, 0xda24260, v152
	v_max_f32_e32 v153, 0xda24260, v153
	v_rcp_f32_e32 v152, v152
	v_rcp_f32_e32 v153, v153
	v_and_b32_e32 v157, 0xffff0000, v154
	v_lshlrev_b32_e32 v154, 16, v155
	v_and_b32_e32 v155, 0xffff0000, v155
	v_pk_mul_f32 v[152:153], v[152:153], v[156:157]
	v_max_f32_e32 v160, 0xda24260, v160
	v_pk_mul_f32 v[88:89], v[88:89], v[152:153]
	v_lshlrev_b32_e32 v152, 16, v159
	v_and_b32_e32 v153, 0xffff0000, v159
	v_max_f32_e32 v152, v152, v152
	v_max_f32_e32 v153, v153, v153
	v_max_f32_e32 v152, 0xda24260, v152
	v_max_f32_e32 v153, 0xda24260, v153
	v_rcp_f32_e32 v152, v152
	v_rcp_f32_e32 v153, v153
	v_rcp_f32_e32 v160, v160
	v_pk_mul_f32 v[184:185], v[184:185], v[186:187]
	v_pk_mul_f32 v[168:169], v[168:169], v[170:171]
	v_pk_mul_f32 v[152:153], v[152:153], v[154:155]
	s_waitcnt vmcnt(5)
	v_lshlrev_b32_e32 v154, 16, v144
	v_pk_mul_f32 v[90:91], v[90:91], v[152:153]
	s_waitcnt vmcnt(4)
	v_lshlrev_b32_e32 v152, 16, v148
	v_and_b32_e32 v148, 0xffff0000, v148
	v_and_b32_e32 v155, 0xffff0000, v144
	v_lshlrev_b32_e32 v144, 16, v149
	v_max_f32_e32 v148, v148, v148
	v_max_f32_e32 v144, v144, v144
	v_max_f32_e32 v148, 0xda24260, v148
	v_max_f32_e32 v144, 0xda24260, v144
	v_rcp_f32_e32 v153, v148
	v_rcp_f32_e32 v148, v144
	v_and_b32_e32 v144, 0xffff0000, v149
	v_max_f32_e32 v144, v144, v144
	v_max_f32_e32 v144, 0xda24260, v144
	v_rcp_f32_e32 v149, v144
	v_lshlrev_b32_e32 v144, 16, v145
	v_and_b32_e32 v145, 0xffff0000, v145
	v_pk_mul_f32 v[160:161], v[160:161], v[162:163]
	v_pk_mul_f32 v[144:145], v[148:149], v[144:145]
	v_lshlrev_b32_e32 v148, 16, v146
	v_pk_mul_f32 v[86:87], v[86:87], v[144:145]
	v_lshlrev_b32_e32 v144, 16, v150
	v_and_b32_e32 v145, 0xffff0000, v150
	v_max_f32_e32 v144, v144, v144
	v_max_f32_e32 v145, v145, v145
	v_max_f32_e32 v144, 0xda24260, v144
	v_max_f32_e32 v145, 0xda24260, v145
	v_rcp_f32_e32 v144, v144
	v_rcp_f32_e32 v145, v145
	v_and_b32_e32 v149, 0xffff0000, v146
	v_lshlrev_b32_e32 v146, 16, v147
	v_and_b32_e32 v147, 0xffff0000, v147
	v_pk_mul_f32 v[144:145], v[144:145], v[148:149]
	v_pk_mul_f32 v[96:97], v[96:97], v[160:161]
	v_pk_mul_f32 v[76:77], v[76:77], v[144:145]
	v_lshlrev_b32_e32 v144, 16, v151
	v_and_b32_e32 v145, 0xffff0000, v151
	v_max_f32_e32 v144, v144, v144
	v_max_f32_e32 v145, v145, v145
	v_max_f32_e32 v144, 0xda24260, v144
	v_max_f32_e32 v145, 0xda24260, v145
	v_rcp_f32_e32 v144, v144
	v_rcp_f32_e32 v145, v145
	v_pk_mul_f32 v[116:117], v[116:117], v[184:185]
	v_pk_mul_f32 v[100:101], v[100:101], v[168:169]
	v_rcp_f32_e32 v238, v219
	v_pk_mul_f32 v[144:145], v[144:145], v[146:147]
	s_waitcnt vmcnt(3)
	v_lshlrev_b32_e32 v146, 16, v136
	v_pk_mul_f32 v[78:79], v[78:79], v[144:145]
	s_waitcnt vmcnt(2)
; __device__ __forceinline__ float bf_lo(unsigned u) { return __uint_as_float(u << 16); }
; __device__ __forceinline__ float bf_hi(unsigned u) { return __uint_as_float(u & 0xffff0000u); }
;     __device__ __forceinline__ void mid(f32x4 (&acc)[2][2][4][2], const Unit& u, int wr, int wc, int fr, int fq) const {
;     ...
;                 for (int bj = 0; bj < 2; ++bj) { sa[m][bj] = *(const u32x4*)(sg + off + m * 16 * 2048 + bj * HALF); sb[m][bj] = *(const u32x4*)(sg + off + m * 16 * 2048 + 1024 + bj * HALF); }
; #pragma unroll
;             for (int m = 0; m < 4; ++m)
; #pragma unroll
;                 for (int bj = 0; bj < 2; ++bj) {
;                     const unsigned av[4] = {sa[m][bj].x, sa[m][bj].y, sa[m][bj].z, sa[m][bj].w}, bv[4] = {sb[m][bj].x, sb[m][bj].y, sb[m][bj].z, sb[m][bj].w};
; #pragma unroll
;                     for (int q = 0; q < 4; ++q) { const float r0 = bf_lo(av[q]) * __builtin_amdgcn_rcpf(fmaxf(bf_lo(bv[q]), 1e-30f)), r1 = bf_hi(av[q]) * __builtin_amdgcn_rcpf(fmaxf(bf_hi(bv[q]), 1e-30f));
;                         acc[ai][bj][m][q >> 1][(q & 1) * 2] *= r0; acc[ai][bj][m][q >> 1][(q & 1) * 2 + 1] *= r1; } }
;             off += 128u * 2048u; }
	v_lshlrev_b32_e32 v144, 16, v140
	v_and_b32_e32 v140, 0xffff0000, v140
	v_and_b32_e32 v147, 0xffff0000, v136
	v_lshlrev_b32_e32 v136, 16, v141
	v_max_f32_e32 v140, v140, v140
	v_max_f32_e32 v136, v136, v136
	v_max_f32_e32 v140, 0xda24260, v140
	v_max_f32_e32 v136, 0xda24260, v136
	v_rcp_f32_e32 v145, v140
	v_rcp_f32_e32 v140, v136
	v_and_b32_e32 v136, 0xffff0000, v141
	v_max_f32_e32 v136, v136, v136
	v_max_f32_e32 v136, 0xda24260, v136
	v_rcp_f32_e32 v141, v136
	v_lshlrev_b32_e32 v136, 16, v137
	v_and_b32_e32 v137, 0xffff0000, v137
	v_pk_mul_f32 v[238:239], v[238:239], v[240:241]
	v_pk_mul_f32 v[136:137], v[140:141], v[136:137]
	v_lshlrev_b32_e32 v140, 16, v138
	v_pk_mul_f32 v[82:83], v[82:83], v[136:137]
	v_lshlrev_b32_e32 v136, 16, v142
	v_and_b32_e32 v137, 0xffff0000, v142
	v_max_f32_e32 v136, v136, v136
	v_max_f32_e32 v137, v137, v137
	v_max_f32_e32 v136, 0xda24260, v136
	v_max_f32_e32 v137, 0xda24260, v137
	v_rcp_f32_e32 v136, v136
	v_rcp_f32_e32 v137, v137
	v_and_b32_e32 v141, 0xffff0000, v138
	v_lshlrev_b32_e32 v138, 16, v139
	v_and_b32_e32 v139, 0xffff0000, v139
	v_pk_mul_f32 v[136:137], v[136:137], v[140:141]
	v_pk_mul_f32 v[124:125], v[124:125], v[238:239]
	v_pk_mul_f32 v[72:73], v[72:73], v[136:137]
	v_lshlrev_b32_e32 v136, 16, v143
	v_and_b32_e32 v137, 0xffff0000, v143
	v_max_f32_e32 v136, v136, v136
	v_max_f32_e32 v137, v137, v137
	v_max_f32_e32 v136, 0xda24260, v136
	v_max_f32_e32 v137, 0xda24260, v137
	v_rcp_f32_e32 v136, v136
	v_rcp_f32_e32 v137, v137
	v_max_f32_e32 v152, v152, v152
	v_max_f32_e32 v144, v144, v144
	v_max_f32_e32 v152, 0xda24260, v152
	v_pk_mul_f32 v[136:137], v[136:137], v[138:139]
	s_waitcnt vmcnt(1)
	v_lshlrev_b32_e32 v138, 16, v128
	v_pk_mul_f32 v[74:75], v[74:75], v[136:137]
	s_waitcnt vmcnt(0)
	v_lshlrev_b32_e32 v136, 16, v132
	v_and_b32_e32 v132, 0xffff0000, v132
	v_and_b32_e32 v139, 0xffff0000, v128
	v_lshlrev_b32_e32 v128, 16, v133
	v_max_f32_e32 v132, v132, v132
	v_max_f32_e32 v128, v128, v128
	v_max_f32_e32 v132, 0xda24260, v132
	v_max_f32_e32 v128, 0xda24260, v128
	v_rcp_f32_e32 v137, v132
	v_rcp_f32_e32 v132, v128
	v_and_b32_e32 v128, 0xffff0000, v133
	v_max_f32_e32 v128, v128, v128
	v_max_f32_e32 v128, 0xda24260, v128
	v_rcp_f32_e32 v133, v128
	v_lshlrev_b32_e32 v128, 16, v129
	v_and_b32_e32 v129, 0xffff0000, v129
	v_max_f32_e32 v144, 0xda24260, v144
	v_pk_mul_f32 v[128:129], v[132:133], v[128:129]
	v_lshlrev_b32_e32 v132, 16, v130
	v_pk_mul_f32 v[70:71], v[70:71], v[128:129]
	v_lshlrev_b32_e32 v128, 16, v134
	v_and_b32_e32 v129, 0xffff0000, v134
	v_max_f32_e32 v128, v128, v128
	v_max_f32_e32 v129, v129, v129
	v_max_f32_e32 v128, 0xda24260, v128
	v_max_f32_e32 v129, 0xda24260, v129
	v_rcp_f32_e32 v128, v128
	v_rcp_f32_e32 v129, v129
	v_and_b32_e32 v133, 0xffff0000, v130
	v_lshlrev_b32_e32 v130, 16, v131
	v_and_b32_e32 v131, 0xffff0000, v131
	v_pk_mul_f32 v[128:129], v[128:129], v[132:133]
	v_rcp_f32_e32 v152, v152
	v_pk_mul_f32 v[64:65], v[64:65], v[128:129]
	v_lshlrev_b32_e32 v128, 16, v135
	v_and_b32_e32 v129, 0xffff0000, v135
	v_max_f32_e32 v128, v128, v128
	v_max_f32_e32 v129, v129, v129
	v_max_f32_e32 v128, 0xda24260, v128
	v_max_f32_e32 v129, 0xda24260, v129
	v_rcp_f32_e32 v128, v128
	v_rcp_f32_e32 v129, v129
	v_rcp_f32_e32 v144, v144
	v_pk_mul_f32 v[152:153], v[152:153], v[154:155]
	v_max_f32_e32 v136, v136, v136
	v_pk_mul_f32 v[128:129], v[128:129], v[130:131]
	v_pk_mul_f32 v[144:145], v[144:145], v[146:147]
	v_pk_mul_f32 v[66:67], v[66:67], v[128:129]
	v_lshl_add_u64 v[128:129], v[194:195], 1, s[10:11]
	global_load_dwordx4 v[172:175], v[128:129], off
	global_load_dwordx4 v[176:179], v[128:129], off offset:2048
	global_load_dwordx4 v[160:163], v[128:129], off offset:256
	global_load_dwordx4 v[188:191], v[128:129], off offset:2304
	v_add_co_u32_e32 v130, vcc, s72, v128
	v_pk_mul_f32 v[84:85], v[84:85], v[152:153]
	s_nop 0
	v_addc_co_u32_e32 v131, vcc, 0, v129, vcc
	global_load_dwordx4 v[180:183], v[130:131], off
	global_load_dwordx4 v[184:187], v[130:131], off offset:2048
	global_load_dwordx4 v[164:167], v[130:131], off offset:256
	global_load_dwordx4 v[168:171], v[130:131], off offset:2304
	v_add_co_u32_e32 v130, vcc, s43, v128
	v_pk_mul_f32 v[80:81], v[80:81], v[144:145]
	s_nop 0
	v_addc_co_u32_e32 v131, vcc, 0, v129, vcc
	global_load_dwordx4 v[152:155], v[130:131], off
	global_load_dwordx4 v[156:159], v[130:131], off offset:2048
	global_load_dwordx4 v[144:147], v[130:131], off offset:256
	global_load_dwordx4 v[148:151], v[130:131], off offset:2304
	v_max_f32_e32 v136, 0xda24260, v136
	v_rcp_f32_e32 v136, v136
	v_add_co_u32_e32 v132, vcc, s60, v128
	v_pk_mul_f32 v[136:137], v[136:137], v[138:139]
	s_nop 0
	v_addc_co_u32_e32 v133, vcc, 0, v129, vcc
	v_pk_mul_f32 v[68:69], v[68:69], v[136:137]
	global_load_dwordx4 v[136:139], v[132:133], off
	global_load_dwordx4 v[140:143], v[132:133], off offset:2048
	global_load_dwordx4 v[128:131], v[132:133], off offset:256
	s_nop 0
	global_load_dwordx4 v[132:135], v[132:133], off offset:2304
	s_waitcnt vmcnt(15)
	v_lshlrev_b32_e32 v240, 16, v172
	s_waitcnt vmcnt(14)
; __device__ __forceinline__ float bf_lo(unsigned u) { return __uint_as_float(u << 16); }
; __device__ __forceinline__ float bf_hi(unsigned u) { return __uint_as_float(u & 0xffff0000u); }
;     __device__ __forceinline__ void mid(f32x4 (&acc)[2][2][4][2], const Unit& u, int wr, int wc, int fr, int fq) const {
;     ...
;             for (int m = 0; m < 4; ++m)
; #pragma unroll
;                 for (int bj = 0; bj < 2; ++bj) {
;                     const unsigned av[4] = {sa[m][bj].x, sa[m][bj].y, sa[m][bj].z, sa[m][bj].w}, bv[4] = {sb[m][bj].x, sb[m][bj].y, sb[m][bj].z, sb[m][bj].w};
; #pragma unroll
;                     for (int q = 0; q < 4; ++q) { const float r0 = bf_lo(av[q]) * __builtin_amdgcn_rcpf(fmaxf(bf_lo(bv[q]), 1e-30f)), r1 = bf_hi(av[q]) * __builtin_amdgcn_rcpf(fmaxf(bf_hi(bv[q]), 1e-30f));
;                         acc[ai][bj][m][q >> 1][(q & 1) * 2] *= r0; acc[ai][bj][m][q >> 1][(q & 1) * 2 + 1] *= r1; } }
	v_lshlrev_b32_e32 v194, 16, v176
	v_and_b32_e32 v176, 0xffff0000, v176
	v_and_b32_e32 v241, 0xffff0000, v172
	v_lshlrev_b32_e32 v172, 16, v177
	v_max_f32_e32 v176, v176, v176
	v_max_f32_e32 v172, v172, v172
	v_max_f32_e32 v176, 0xda24260, v176
	v_max_f32_e32 v172, 0xda24260, v172
	v_rcp_f32_e32 v239, v176
	v_rcp_f32_e32 v176, v172
	v_and_b32_e32 v172, 0xffff0000, v177
	v_max_f32_e32 v172, v172, v172
	v_max_f32_e32 v172, 0xda24260, v172
	v_rcp_f32_e32 v177, v172
	v_lshlrev_b32_e32 v172, 16, v173
	v_and_b32_e32 v173, 0xffff0000, v173
	v_max_f32_e32 v194, v194, v194
	v_pk_mul_f32 v[172:173], v[176:177], v[172:173]
	v_lshlrev_b32_e32 v176, 16, v174
	v_pk_mul_f32 v[62:63], v[62:63], v[172:173]
	v_lshlrev_b32_e32 v172, 16, v178
	v_and_b32_e32 v173, 0xffff0000, v178
	v_max_f32_e32 v172, v172, v172
	v_max_f32_e32 v173, v173, v173
	v_max_f32_e32 v172, 0xda24260, v172
	v_max_f32_e32 v173, 0xda24260, v173
	v_rcp_f32_e32 v172, v172
	v_rcp_f32_e32 v173, v173
	v_and_b32_e32 v177, 0xffff0000, v174
	v_lshlrev_b32_e32 v174, 16, v175
	v_and_b32_e32 v175, 0xffff0000, v175
	v_pk_mul_f32 v[172:173], v[172:173], v[176:177]
	v_max_f32_e32 v194, 0xda24260, v194
	v_pk_mul_f32 v[56:57], v[56:57], v[172:173]
	v_lshlrev_b32_e32 v172, 16, v179
	v_and_b32_e32 v173, 0xffff0000, v179
	v_max_f32_e32 v172, v172, v172
	v_max_f32_e32 v173, v173, v173
	v_max_f32_e32 v172, 0xda24260, v172
	v_max_f32_e32 v173, 0xda24260, v173
	v_rcp_f32_e32 v172, v172
	v_rcp_f32_e32 v173, v173
	v_rcp_f32_e32 v238, v194
	v_pk_mul_f32 v[172:173], v[172:173], v[174:175]
	s_nop 0
	v_pk_mul_f32 v[58:59], v[58:59], v[172:173]
	s_waitcnt vmcnt(12)
	v_lshlrev_b32_e32 v172, 16, v188
	v_and_b32_e32 v173, 0xffff0000, v188
	v_max_f32_e32 v172, v172, v172
	v_max_f32_e32 v173, v173, v173
	v_max_f32_e32 v172, 0xda24260, v172
	v_max_f32_e32 v173, 0xda24260, v173
	v_rcp_f32_e32 v172, v172
	v_rcp_f32_e32 v173, v173
	v_lshlrev_b32_e32 v174, 16, v160
	v_and_b32_e32 v175, 0xffff0000, v160
	v_lshlrev_b32_e32 v160, 16, v189
	v_max_f32_e32 v160, v160, v160
	v_pk_mul_f32 v[172:173], v[172:173], v[174:175]
	v_max_f32_e32 v160, 0xda24260, v160
	v_pk_mul_f32 v[52:53], v[52:53], v[172:173]
	v_rcp_f32_e32 v172, v160
	v_and_b32_e32 v160, 0xffff0000, v189
	v_max_f32_e32 v160, v160, v160
	v_max_f32_e32 v160, 0xda24260, v160
	v_rcp_f32_e32 v173, v160
	v_lshlrev_b32_e32 v160, 16, v161
	v_and_b32_e32 v161, 0xffff0000, v161
	v_pk_mul_f32 v[238:239], v[238:239], v[240:241]
	v_pk_mul_f32 v[160:161], v[172:173], v[160:161]
	v_lshlrev_b32_e32 v172, 16, v162
	v_pk_mul_f32 v[54:55], v[54:55], v[160:161]
	v_lshlrev_b32_e32 v160, 16, v190
	v_and_b32_e32 v161, 0xffff0000, v190
	v_max_f32_e32 v160, v160, v160
	v_max_f32_e32 v161, v161, v161
	v_max_f32_e32 v160, 0xda24260, v160
	v_max_f32_e32 v161, 0xda24260, v161
	v_rcp_f32_e32 v160, v160
	v_rcp_f32_e32 v161, v161
	v_and_b32_e32 v173, 0xffff0000, v162
	v_lshlrev_b32_e32 v162, 16, v163
	v_and_b32_e32 v163, 0xffff0000, v163
	v_pk_mul_f32 v[160:161], v[160:161], v[172:173]
	v_pk_mul_f32 v[60:61], v[60:61], v[238:239]
	v_pk_mul_f32 v[44:45], v[44:45], v[160:161]
	v_lshlrev_b32_e32 v160, 16, v191
	v_and_b32_e32 v161, 0xffff0000, v191
	v_max_f32_e32 v160, v160, v160
	v_max_f32_e32 v161, v161, v161
	v_max_f32_e32 v160, 0xda24260, v160
	v_max_f32_e32 v161, 0xda24260, v161
	v_rcp_f32_e32 v160, v160
	v_rcp_f32_e32 v161, v161
	s_nop 0
	v_pk_mul_f32 v[160:161], v[160:161], v[162:163]
	s_nop 0
	v_pk_mul_f32 v[46:47], v[46:47], v[160:161]
	s_waitcnt vmcnt(10)
	v_lshlrev_b32_e32 v160, 16, v184
	v_and_b32_e32 v161, 0xffff0000, v184
	v_max_f32_e32 v160, v160, v160
	v_max_f32_e32 v161, v161, v161
	v_max_f32_e32 v160, 0xda24260, v160
	v_max_f32_e32 v161, 0xda24260, v161
	v_rcp_f32_e32 v160, v160
	v_rcp_f32_e32 v161, v161
	v_lshlrev_b32_e32 v162, 16, v180
	v_and_b32_e32 v163, 0xffff0000, v180
	v_pk_mul_f32 v[160:161], v[160:161], v[162:163]
	s_nop 0
	v_pk_mul_f32 v[48:49], v[48:49], v[160:161]
	v_lshlrev_b32_e32 v160, 16, v185
	v_and_b32_e32 v161, 0xffff0000, v185
	v_max_f32_e32 v160, v160, v160
	v_max_f32_e32 v161, v161, v161
	v_max_f32_e32 v160, 0xda24260, v160
	v_max_f32_e32 v161, 0xda24260, v161
	v_rcp_f32_e32 v160, v160
	v_rcp_f32_e32 v161, v161
	v_lshlrev_b32_e32 v162, 16, v181
	v_and_b32_e32 v163, 0xffff0000, v181
	v_pk_mul_f32 v[160:161], v[160:161], v[162:163]
	s_nop 0
	v_pk_mul_f32 v[50:51], v[50:51], v[160:161]
	v_lshlrev_b32_e32 v160, 16, v186
	v_and_b32_e32 v161, 0xffff0000, v186
	v_max_f32_e32 v160, v160, v160
	v_max_f32_e32 v161, v161, v161
	v_max_f32_e32 v160, 0xda24260, v160
	v_max_f32_e32 v161, 0xda24260, v161
	v_rcp_f32_e32 v160, v160
	v_rcp_f32_e32 v161, v161
	v_lshlrev_b32_e32 v162, 16, v182
	v_and_b32_e32 v163, 0xffff0000, v182
	v_pk_mul_f32 v[160:161], v[160:161], v[162:163]
	s_nop 0
	v_pk_mul_f32 v[40:41], v[40:41], v[160:161]
	v_lshlrev_b32_e32 v160, 16, v187
	v_and_b32_e32 v161, 0xffff0000, v187
	v_max_f32_e32 v160, v160, v160
	v_max_f32_e32 v161, v161, v161
	v_max_f32_e32 v160, 0xda24260, v160
	v_max_f32_e32 v161, 0xda24260, v161
	v_rcp_f32_e32 v160, v160
	v_rcp_f32_e32 v161, v161
	v_lshlrev_b32_e32 v162, 16, v183
	v_and_b32_e32 v163, 0xffff0000, v183
	v_pk_mul_f32 v[160:161], v[160:161], v[162:163]
	s_nop 0
	v_pk_mul_f32 v[42:43], v[42:43], v[160:161]
	s_waitcnt vmcnt(8)
; __device__ __forceinline__ float bf_lo(unsigned u) { return __uint_as_float(u << 16); }
; __device__ __forceinline__ float bf_hi(unsigned u) { return __uint_as_float(u & 0xffff0000u); }
;     __device__ __forceinline__ void mid(f32x4 (&acc)[2][2][4][2], const Unit& u, int wr, int wc, int fr, int fq) const {
;     ...
;             for (int m = 0; m < 4; ++m)
; #pragma unroll
;                 for (int bj = 0; bj < 2; ++bj) {
;                     const unsigned av[4] = {sa[m][bj].x, sa[m][bj].y, sa[m][bj].z, sa[m][bj].w}, bv[4] = {sb[m][bj].x, sb[m][bj].y, sb[m][bj].z, sb[m][bj].w};
; #pragma unroll
;                     for (int q = 0; q < 4; ++q) { const float r0 = bf_lo(av[q]) * __builtin_amdgcn_rcpf(fmaxf(bf_lo(bv[q]), 1e-30f)), r1 = bf_hi(av[q]) * __builtin_amdgcn_rcpf(fmaxf(bf_hi(bv[q]), 1e-30f));
;                         acc[ai][bj][m][q >> 1][(q & 1) * 2] *= r0; acc[ai][bj][m][q >> 1][(q & 1) * 2 + 1] *= r1; } }
	v_lshlrev_b32_e32 v160, 16, v168
	v_and_b32_e32 v161, 0xffff0000, v168
	v_max_f32_e32 v160, v160, v160
	v_max_f32_e32 v161, v161, v161
	v_max_f32_e32 v160, 0xda24260, v160
	v_max_f32_e32 v161, 0xda24260, v161
	v_rcp_f32_e32 v160, v160
	v_rcp_f32_e32 v161, v161
	v_lshlrev_b32_e32 v162, 16, v164
	v_and_b32_e32 v163, 0xffff0000, v164
	v_pk_mul_f32 v[160:161], v[160:161], v[162:163]
	s_nop 0
	v_pk_mul_f32 v[36:37], v[36:37], v[160:161]
	v_lshlrev_b32_e32 v160, 16, v169
	v_and_b32_e32 v161, 0xffff0000, v169
	v_max_f32_e32 v160, v160, v160
	v_max_f32_e32 v161, v161, v161
	v_max_f32_e32 v160, 0xda24260, v160
	v_max_f32_e32 v161, 0xda24260, v161
	v_rcp_f32_e32 v160, v160
	v_rcp_f32_e32 v161, v161
	v_lshlrev_b32_e32 v162, 16, v165
	v_and_b32_e32 v163, 0xffff0000, v165
	v_pk_mul_f32 v[160:161], v[160:161], v[162:163]
	s_nop 0
	v_pk_mul_f32 v[38:39], v[38:39], v[160:161]
	v_lshlrev_b32_e32 v160, 16, v170
	v_and_b32_e32 v161, 0xffff0000, v170
	v_max_f32_e32 v160, v160, v160
	v_max_f32_e32 v161, v161, v161
	v_max_f32_e32 v160, 0xda24260, v160
	v_max_f32_e32 v161, 0xda24260, v161
	v_rcp_f32_e32 v160, v160
	v_rcp_f32_e32 v161, v161
	v_lshlrev_b32_e32 v162, 16, v166
	v_and_b32_e32 v163, 0xffff0000, v166
	v_pk_mul_f32 v[160:161], v[160:161], v[162:163]
	s_nop 0
	v_pk_mul_f32 v[28:29], v[28:29], v[160:161]
	v_lshlrev_b32_e32 v160, 16, v171
	v_and_b32_e32 v161, 0xffff0000, v171
	v_max_f32_e32 v160, v160, v160
	v_max_f32_e32 v161, v161, v161
	v_max_f32_e32 v160, 0xda24260, v160
	v_max_f32_e32 v161, 0xda24260, v161
	v_rcp_f32_e32 v160, v160
	v_rcp_f32_e32 v161, v161
	v_lshlrev_b32_e32 v162, 16, v167
	v_and_b32_e32 v163, 0xffff0000, v167
	v_pk_mul_f32 v[160:161], v[160:161], v[162:163]
	s_nop 0
	v_pk_mul_f32 v[30:31], v[30:31], v[160:161]
	s_waitcnt vmcnt(6)
	v_lshlrev_b32_e32 v160, 16, v156
	v_and_b32_e32 v156, 0xffff0000, v156
	v_lshlrev_b32_e32 v162, 16, v152
	v_and_b32_e32 v163, 0xffff0000, v152
	v_lshlrev_b32_e32 v152, 16, v157
	v_max_f32_e32 v156, v156, v156
	v_max_f32_e32 v152, v152, v152
	v_max_f32_e32 v156, 0xda24260, v156
	v_max_f32_e32 v152, 0xda24260, v152
	v_rcp_f32_e32 v161, v156
	v_rcp_f32_e32 v156, v152
	v_and_b32_e32 v152, 0xffff0000, v157
	v_max_f32_e32 v152, v152, v152
	v_max_f32_e32 v152, 0xda24260, v152
	v_rcp_f32_e32 v157, v152
	v_lshlrev_b32_e32 v152, 16, v153
	v_and_b32_e32 v153, 0xffff0000, v153
	v_max_f32_e32 v160, v160, v160
	v_pk_mul_f32 v[152:153], v[156:157], v[152:153]
	v_lshlrev_b32_e32 v156, 16, v154
	v_pk_mul_f32 v[34:35], v[34:35], v[152:153]
	v_lshlrev_b32_e32 v152, 16, v158
	v_and_b32_e32 v153, 0xffff0000, v158
	v_max_f32_e32 v152, v152, v152
	v_max_f32_e32 v153, v153, v153
	v_max_f32_e32 v152, 0xda24260, v152
	v_max_f32_e32 v153, 0xda24260, v153
	v_rcp_f32_e32 v152, v152
	v_rcp_f32_e32 v153, v153
	v_and_b32_e32 v157, 0xffff0000, v154
	v_lshlrev_b32_e32 v154, 16, v155
	v_and_b32_e32 v155, 0xffff0000, v155
	v_pk_mul_f32 v[152:153], v[152:153], v[156:157]
	v_max_f32_e32 v160, 0xda24260, v160
	v_pk_mul_f32 v[24:25], v[24:25], v[152:153]
	v_lshlrev_b32_e32 v152, 16, v159
	v_and_b32_e32 v153, 0xffff0000, v159
	v_max_f32_e32 v152, v152, v152
	v_max_f32_e32 v153, v153, v153
	v_max_f32_e32 v152, 0xda24260, v152
	v_max_f32_e32 v153, 0xda24260, v153
	v_rcp_f32_e32 v152, v152
	v_rcp_f32_e32 v153, v153
	v_rcp_f32_e32 v160, v160
	v_pk_mul_f32 v[152:153], v[152:153], v[154:155]
	s_nop 0
	v_pk_mul_f32 v[26:27], v[26:27], v[152:153]
	s_waitcnt vmcnt(4)
	v_lshlrev_b32_e32 v152, 16, v148
	v_and_b32_e32 v148, 0xffff0000, v148
	v_lshlrev_b32_e32 v154, 16, v144
	v_and_b32_e32 v155, 0xffff0000, v144
	v_lshlrev_b32_e32 v144, 16, v149
	v_max_f32_e32 v148, v148, v148
	v_max_f32_e32 v144, v144, v144
	v_max_f32_e32 v148, 0xda24260, v148
	v_max_f32_e32 v144, 0xda24260, v144
	v_rcp_f32_e32 v153, v148
	v_rcp_f32_e32 v148, v144
	v_and_b32_e32 v144, 0xffff0000, v149
	v_max_f32_e32 v144, v144, v144
	v_max_f32_e32 v144, 0xda24260, v144
	v_rcp_f32_e32 v149, v144
	v_lshlrev_b32_e32 v144, 16, v145
	v_and_b32_e32 v145, 0xffff0000, v145
	v_max_f32_e32 v152, v152, v152
	v_pk_mul_f32 v[144:145], v[148:149], v[144:145]
	v_lshlrev_b32_e32 v148, 16, v146
	v_pk_mul_f32 v[22:23], v[22:23], v[144:145]
	v_lshlrev_b32_e32 v144, 16, v150
	v_and_b32_e32 v145, 0xffff0000, v150
	v_max_f32_e32 v144, v144, v144
	v_max_f32_e32 v145, v145, v145
	v_max_f32_e32 v144, 0xda24260, v144
	v_max_f32_e32 v145, 0xda24260, v145
	v_rcp_f32_e32 v144, v144
	v_rcp_f32_e32 v145, v145
	v_and_b32_e32 v149, 0xffff0000, v146
	v_lshlrev_b32_e32 v146, 16, v147
	v_and_b32_e32 v147, 0xffff0000, v147
	v_pk_mul_f32 v[144:145], v[144:145], v[148:149]
	v_max_f32_e32 v152, 0xda24260, v152
	v_pk_mul_f32 v[12:13], v[12:13], v[144:145]
	v_lshlrev_b32_e32 v144, 16, v151
	v_and_b32_e32 v145, 0xffff0000, v151
	v_max_f32_e32 v144, v144, v144
	v_max_f32_e32 v145, v145, v145
	v_max_f32_e32 v144, 0xda24260, v144
	v_max_f32_e32 v145, 0xda24260, v145
	v_rcp_f32_e32 v144, v144
	v_rcp_f32_e32 v145, v145
	v_rcp_f32_e32 v152, v152
	v_pk_mul_f32 v[160:161], v[160:161], v[162:163]
	v_pk_mul_f32 v[144:145], v[144:145], v[146:147]
	s_nop 0
	v_pk_mul_f32 v[14:15], v[14:15], v[144:145]
	s_waitcnt vmcnt(2)
; __device__ __forceinline__ float bf_lo(unsigned u) { return __uint_as_float(u << 16); }
; __device__ __forceinline__ float bf_hi(unsigned u) { return __uint_as_float(u & 0xffff0000u); }
; #define PG8_LDA(dst, b, h) do { _Pragma("unroll") for (int m = 0; m < 4; ++m) _Pragma("unroll") for (int k = 0; k < 2; ++k) dst[m][k] = *(const LAS bf16x8*)(lds + PG8_SA(b, h) + aoff + m * 2048 + k * 1024); } while (0)
; #define PG8_LDB(dst, b, h) do { _Pragma("unroll") for (int n = 0; n < 2; ++n) _Pragma("unroll") for (int k = 0; k < 2; ++k) dst[n][k] = *(const LAS bf16x8*)(lds + PG8_SB(b, h) + boff + n * 2048 + k * 1024); } while (0)
; #define PG8_WAIT_V(n) asm volatile("s_waitcnt vmcnt(" #n ")" ::: "memory")
; template <class Epi, bool GATHER = false>
; __device__ __forceinline__ void gemm_phase(LAS unsigned char* lds, const Gemm g, const Order& S, const Epi& E, const int* gidx = nullptr) {
;     ...
;         for (int t = 0; t < nt; t += 2) {
;             const bool last = (t == nt - 2);
;             if constexpr (Epi::HAS_MID) { if (t == Epi::MID_T) { PG8_SCHED; E.mid(acc, cur, wr, wc, fr, fq); PG8_SCHED; } }
;             const char* a1 = cA + (size_t)(t + 1) * kstep;
;             const char* a2 = last ? nA : cA + (size_t)(t + 2) * kstep; const char* b2 = last ? nB : cB + (size_t)(t + 2) * kstep;
;             const char* a3 = a2 + kstep; const char* b3 = b2 + kstep;
;             PG8_LDB(B0, 0, 0); PG8_LDB(B1, 0, 1); PG8_SCHED; PG8_LDA(At, 0, 0); PG8_STAGE_A(PG8_SA(1, 1), a1, 1, false);
;             PG8_WAIT_V(8); PG8_WAIT_L(0); PG8_BAR; PG8_MMA(0, 0, At, B0); PG8_MMA(0, 1, At, B1); PG8_BAR; PG8_SCHED;
;     __device__ __forceinline__ void mid(f32x4 (&acc)[2][2][4][2], const Unit& u, int wr, int wc, int fr, int fq) const {
;     ...
;             for (int m = 0; m < 4; ++m)
; #pragma unroll
;                 for (int bj = 0; bj < 2; ++bj) {
;                     const unsigned av[4] = {sa[m][bj].x, sa[m][bj].y, sa[m][bj].z, sa[m][bj].w}, bv[4] = {sb[m][bj].x, sb[m][bj].y, sb[m][bj].z, sb[m][bj].w};
; #pragma unroll
;                     for (int q = 0; q < 4; ++q) { const float r0 = bf_lo(av[q]) * __builtin_amdgcn_rcpf(fmaxf(bf_lo(bv[q]), 1e-30f)), r1 = bf_hi(av[q]) * __builtin_amdgcn_rcpf(fmaxf(bf_hi(bv[q]), 1e-30f));
;                         acc[ai][bj][m][q >> 1][(q & 1) * 2] *= r0; acc[ai][bj][m][q >> 1][(q & 1) * 2 + 1] *= r1; } }
;             off += 128u * 2048u; }
	v_lshlrev_b32_e32 v144, 16, v140
	v_and_b32_e32 v140, 0xffff0000, v140
	v_lshlrev_b32_e32 v146, 16, v136
	v_and_b32_e32 v147, 0xffff0000, v136
	v_lshlrev_b32_e32 v136, 16, v141
	v_max_f32_e32 v140, v140, v140
	v_max_f32_e32 v136, v136, v136
	v_max_f32_e32 v140, 0xda24260, v140
	v_max_f32_e32 v136, 0xda24260, v136
	v_rcp_f32_e32 v145, v140
	v_rcp_f32_e32 v140, v136
	v_and_b32_e32 v136, 0xffff0000, v141
	v_max_f32_e32 v136, v136, v136
	v_max_f32_e32 v136, 0xda24260, v136
	v_rcp_f32_e32 v141, v136
	v_lshlrev_b32_e32 v136, 16, v137
	v_and_b32_e32 v137, 0xffff0000, v137
	v_max_f32_e32 v144, v144, v144
	v_pk_mul_f32 v[136:137], v[140:141], v[136:137]
	v_lshlrev_b32_e32 v140, 16, v138
	v_pk_mul_f32 v[18:19], v[18:19], v[136:137]
	v_lshlrev_b32_e32 v136, 16, v142
	v_and_b32_e32 v137, 0xffff0000, v142
	v_max_f32_e32 v136, v136, v136
	v_max_f32_e32 v137, v137, v137
	v_max_f32_e32 v136, 0xda24260, v136
	v_max_f32_e32 v137, 0xda24260, v137
	v_rcp_f32_e32 v136, v136
	v_rcp_f32_e32 v137, v137
	v_and_b32_e32 v141, 0xffff0000, v138
	v_lshlrev_b32_e32 v138, 16, v139
	v_and_b32_e32 v139, 0xffff0000, v139
	v_pk_mul_f32 v[136:137], v[136:137], v[140:141]
	v_max_f32_e32 v144, 0xda24260, v144
	v_pk_mul_f32 v[8:9], v[8:9], v[136:137]
	v_lshlrev_b32_e32 v136, 16, v143
	v_and_b32_e32 v137, 0xffff0000, v143
	v_max_f32_e32 v136, v136, v136
	v_max_f32_e32 v137, v137, v137
	v_max_f32_e32 v136, 0xda24260, v136
	v_max_f32_e32 v137, 0xda24260, v137
	v_rcp_f32_e32 v136, v136
	v_rcp_f32_e32 v137, v137
	v_rcp_f32_e32 v144, v144
	v_pk_mul_f32 v[152:153], v[152:153], v[154:155]
	v_pk_mul_f32 v[32:33], v[32:33], v[160:161]
	v_pk_mul_f32 v[136:137], v[136:137], v[138:139]
	s_waitcnt vmcnt(1)
	v_lshlrev_b32_e32 v138, 16, v128
	v_pk_mul_f32 v[10:11], v[10:11], v[136:137]
	s_waitcnt vmcnt(0)
	v_lshlrev_b32_e32 v136, 16, v132
	v_and_b32_e32 v132, 0xffff0000, v132
	v_and_b32_e32 v139, 0xffff0000, v128
	v_lshlrev_b32_e32 v128, 16, v133
	v_max_f32_e32 v132, v132, v132
	v_max_f32_e32 v128, v128, v128
	v_max_f32_e32 v132, 0xda24260, v132
	v_max_f32_e32 v128, 0xda24260, v128
	v_rcp_f32_e32 v137, v132
	v_rcp_f32_e32 v132, v128
	v_and_b32_e32 v128, 0xffff0000, v133
	v_max_f32_e32 v128, v128, v128
	v_max_f32_e32 v128, 0xda24260, v128
	v_rcp_f32_e32 v133, v128
	v_lshlrev_b32_e32 v128, 16, v129
	v_and_b32_e32 v129, 0xffff0000, v129
	v_max_f32_e32 v136, v136, v136
	v_pk_mul_f32 v[128:129], v[132:133], v[128:129]
	v_lshlrev_b32_e32 v132, 16, v130
	v_pk_mul_f32 v[6:7], v[6:7], v[128:129]
	v_lshlrev_b32_e32 v128, 16, v134
	v_and_b32_e32 v129, 0xffff0000, v134
	v_max_f32_e32 v128, v128, v128
	v_max_f32_e32 v129, v129, v129
	v_max_f32_e32 v128, 0xda24260, v128
	v_max_f32_e32 v129, 0xda24260, v129
	v_rcp_f32_e32 v128, v128
	v_rcp_f32_e32 v129, v129
	v_and_b32_e32 v133, 0xffff0000, v130
	v_max_f32_e32 v136, 0xda24260, v136
	v_rcp_f32_e32 v136, v136
	v_pk_mul_f32 v[128:129], v[128:129], v[132:133]
	v_lshlrev_b32_e32 v130, 16, v131
	v_pk_mul_f32 v[0:1], v[0:1], v[128:129]
	v_lshlrev_b32_e32 v128, 16, v135
	v_and_b32_e32 v129, 0xffff0000, v135
	v_max_f32_e32 v128, v128, v128
	v_max_f32_e32 v129, v129, v129
	v_max_f32_e32 v128, 0xda24260, v128
	v_max_f32_e32 v129, 0xda24260, v129
	v_rcp_f32_e32 v128, v128
	v_rcp_f32_e32 v129, v129
	v_and_b32_e32 v131, 0xffff0000, v131
	v_pk_mul_f32 v[144:145], v[144:145], v[146:147]
	v_pk_mul_f32 v[136:137], v[136:137], v[138:139]
	v_pk_mul_f32 v[128:129], v[128:129], v[130:131]
	v_pk_mul_f32 v[20:21], v[20:21], v[152:153]
	v_pk_mul_f32 v[16:17], v[16:17], v[144:145]
	v_pk_mul_f32 v[4:5], v[4:5], v[136:137]
	v_pk_mul_f32 v[2:3], v[2:3], v[128:129]
	s_branch .LBB0_422
